# P4 epilogue: store addresses stepped with one 64-bit add per store from the first address (pitch*16 / pitch*80 in SGPR pairs) instead of 11 64-bit multiply-adds per tile
# speedup vs baseline: 1.0018x; 1.0018x over previous
; __device__ __forceinline__ u32x4 pack8(const f32x4 a, const f32x4 b) { u32x4 w; w.x = cvt_pk_bf16(a[0], a[1]); w.y = cvt_pk_bf16(a[2], a[3]); w.z = cvt_pk_bf16(b[0], b[1]); w.w = cvt_pk_bf16(b[2], b[3]); return w; }
;     __device__ __forceinline__ void operator()(const f32x4 (&acc)[2][2][4][2], const Unit& u, int wr, int wc, int fr, int fq) const {
;     ...
; #pragma unroll
;         for (int ai = 0; ai < 2; ++ai)
; #pragma unroll
;             for (int m = 0; m < 4; ++m) { const int row = row0 + ai * HALF + m * 16; const float r = rs[ai][m]; f32x4 v[2];
;                 const float r2 = -LOG2E * r, ir2 = __builtin_amdgcn_rcpf(r * r);
; #pragma unroll
;                 for (int n = 0; n < 2; ++n) { const f32x4 gt = acc[ai][0][m][n], up = acc[ai][1][m][n];
;                     const f32x4 t = gt * r2, gu = gt * up; f32x4 ex = (f32x4){__builtin_amdgcn_exp2f(t[0]), __builtin_amdgcn_exp2f(t[1]), __builtin_amdgcn_exp2f(t[2]), __builtin_amdgcn_exp2f(t[3])};
;                     const f32x4 den = ex * ir2 + ir2; const f32x4 rc = (f32x4){__builtin_amdgcn_rcpf(den[0]), __builtin_amdgcn_rcpf(den[1]), __builtin_amdgcn_rcpf(den[2]), __builtin_amdgcn_rcpf(den[3])};
;                     v[n] = gu * rc; }
;                 *(u32x4*)(HM + (size_t)row * FF + col0) = pack8(v[0], v[1]); }
.LBB0_745:
	s_lshl_b32 s84, s63, 4
	s_mov_b32 s85, 0
	s_mul_i32 s86, s63, 0x50
	s_mov_b32 s87, 0
	v_mul_f32_e32 v174, 0xbfb8aa3b, v174
	v_pk_mul_f32 v[176:177], v[176:177], v[176:177]
	v_pk_mul_f32 v[202:203], v[126:127], v[174:175] op_sel_hi:[1,0]
	v_rcp_f32_e32 v198, v177
	v_exp_f32_e32 v202, v202
	v_exp_f32_e32 v203, v203
	v_pk_mul_f32 v[200:201], v[128:129], v[174:175] op_sel_hi:[1,0]
	v_pk_mul_f32 v[124:125], v[128:129], v[124:125]
	v_exp_f32_e32 v200, v200
	v_exp_f32_e32 v201, v201
	v_pk_fma_f32 v[128:129], v[198:199], v[202:203], v[198:199] op_sel_hi:[0,1,0]
	v_pk_mul_f32 v[202:203], v[118:119], v[174:175] op_sel_hi:[1,0]
	v_rcp_f32_e32 v128, v128
	v_rcp_f32_e32 v129, v129
	v_exp_f32_e32 v202, v202
	v_exp_f32_e32 v203, v203
	v_pk_mul_f32 v[122:123], v[126:127], v[122:123]
	v_pk_fma_f32 v[126:127], v[198:199], v[200:201], v[198:199] op_sel_hi:[0,1,0]
	v_pk_mul_f32 v[200:201], v[120:121], v[174:175] op_sel_hi:[1,0]
	v_rcp_f32_e32 v126, v126
	v_rcp_f32_e32 v127, v127
	v_exp_f32_e32 v200, v200
	v_exp_f32_e32 v201, v201
	v_pk_mul_f32 v[122:123], v[122:123], v[128:129]
	v_pk_fma_f32 v[128:129], v[198:199], v[202:203], v[198:199] op_sel_hi:[0,1,0]
	v_rcp_f32_e32 v128, v128
	v_rcp_f32_e32 v129, v129
	v_pk_mul_f32 v[124:125], v[124:125], v[126:127]
	v_pk_fma_f32 v[126:127], v[198:199], v[200:201], v[198:199] op_sel_hi:[0,1,0]
	v_rcp_f32_e32 v126, v126
	v_rcp_f32_e32 v127, v127
	v_pk_mul_f32 v[114:115], v[118:119], v[114:115]
	v_pk_mul_f32 v[116:117], v[120:121], v[116:117]
	v_pk_mul_f32 v[114:115], v[114:115], v[128:129]
	v_cvt_pk_bf16_f32 v118, v122, v123
	v_cvt_pk_bf16_f32 v119, v124, v125
	v_pk_mul_f32 v[116:117], v[116:117], v[126:127]
	v_cvt_pk_bf16_f32 v120, v114, v115
	v_mov_b64_e32 v[114:115], s[28:29]
	v_mad_u64_u32 v[122:123], s[0:1], v162, s63, v[114:115]
	v_lshl_or_b32 v168, s64, 7, v194
	v_cvt_pk_bf16_f32 v121, v116, v117
	v_mov_b32_e32 v116, v123
	v_ashrrev_i32_e32 v169, 31, v168
	v_mad_u64_u32 v[116:117], s[0:1], v163, s63, v[116:117]
	v_mov_b32_e32 v123, v116
	v_lshlrev_b64 v[116:117], 1, v[168:169]
	v_lshl_add_u64 v[122:123], v[122:123], 0, v[116:117]
	v_mov_b64_e32 v[250:251], v[122:123]
	global_store_dwordx4 v[122:123], v[118:121], off
	v_pk_mul_f32 v[108:109], v[112:113], v[108:109]
	v_pk_mul_f32 v[106:107], v[110:111], v[106:107]
	v_mul_f32_e32 v118, 0xbfb8aa3b, v175
	v_pk_mul_f32 v[122:123], v[112:113], v[118:119] op_sel_hi:[1,0]
	v_pk_mul_f32 v[124:125], v[110:111], v[118:119] op_sel_hi:[1,0]
	v_rcp_f32_e32 v120, v176
	v_exp_f32_e32 v124, v124
	v_exp_f32_e32 v122, v122
	v_exp_f32_e32 v123, v123
	v_exp_f32_e32 v125, v125
	v_pk_mul_f32 v[100:101], v[104:105], v[100:101]
	v_pk_mul_f32 v[98:99], v[102:103], v[98:99]
	v_pk_fma_f32 v[110:111], v[120:121], v[122:123], v[120:121] op_sel_hi:[0,1,0]
	v_pk_fma_f32 v[112:113], v[120:121], v[124:125], v[120:121] op_sel_hi:[0,1,0]
	v_pk_mul_f32 v[122:123], v[104:105], v[118:119] op_sel_hi:[1,0]
	v_pk_mul_f32 v[118:119], v[102:103], v[118:119] op_sel_hi:[1,0]
	v_rcp_f32_e32 v112, v112
	v_rcp_f32_e32 v113, v113
	v_rcp_f32_e32 v110, v110
	v_rcp_f32_e32 v111, v111
	v_exp_f32_e32 v118, v118
	v_exp_f32_e32 v122, v122
	v_exp_f32_e32 v123, v123
	v_exp_f32_e32 v119, v119
	v_pk_mul_f32 v[108:109], v[108:109], v[110:111]
	v_pk_mul_f32 v[106:107], v[106:107], v[112:113]
	v_pk_fma_f32 v[110:111], v[120:121], v[122:123], v[120:121] op_sel_hi:[0,1,0]
	v_pk_fma_f32 v[112:113], v[120:121], v[118:119], v[120:121] op_sel_hi:[0,1,0]
	v_rcp_f32_e32 v112, v112
	v_rcp_f32_e32 v110, v110
	v_rcp_f32_e32 v111, v111
	v_rcp_f32_e32 v113, v113
	v_pk_mul_f32 v[92:93], v[96:97], v[92:93]
	v_pk_mul_f32 v[90:91], v[94:95], v[90:91]
	v_pk_mul_f32 v[102:103], v[100:101], v[110:111]
	v_pk_mul_f32 v[100:101], v[98:99], v[112:113]
	v_cvt_pk_bf16_f32 v98, v106, v107
	v_cvt_pk_bf16_f32 v99, v108, v109
	v_pk_mul_f32 v[84:85], v[88:89], v[84:85]
	v_cvt_pk_bf16_f32 v100, v100, v101
	v_cvt_pk_bf16_f32 v101, v102, v103
	v_lshl_add_u64 v[250:251], s[84:85], 0, v[250:251]
	global_store_dwordx4 v[250:251], v[98:101], off
	v_pk_mul_f32 v[82:83], v[86:87], v[82:83]
	v_pk_mul_f32 v[76:77], v[80:81], v[76:77]
	v_mul_f32_e32 v98, 0xbfb8aa3b, v170
	v_pk_mul_f32 v[100:101], v[172:173], v[172:173]
	v_pk_mul_f32 v[104:105], v[96:97], v[98:99] op_sel_hi:[1,0]
	v_pk_mul_f32 v[106:107], v[94:95], v[98:99] op_sel_hi:[1,0]
	v_rcp_f32_e32 v102, v101
	v_exp_f32_e32 v106, v106
	v_exp_f32_e32 v104, v104
	v_exp_f32_e32 v105, v105
	v_exp_f32_e32 v107, v107
	v_pk_mul_f32 v[74:75], v[78:79], v[74:75]
	v_pk_mul_f32 v[68:69], v[72:73], v[68:69]
	v_pk_fma_f32 v[94:95], v[102:103], v[104:105], v[102:103] op_sel_hi:[0,1,0]
	v_pk_fma_f32 v[96:97], v[102:103], v[106:107], v[102:103] op_sel_hi:[0,1,0]
	v_pk_mul_f32 v[104:105], v[88:89], v[98:99] op_sel_hi:[1,0]
	v_pk_mul_f32 v[98:99], v[86:87], v[98:99] op_sel_hi:[1,0]
	v_rcp_f32_e32 v96, v96
	v_rcp_f32_e32 v97, v97
	v_rcp_f32_e32 v94, v94
	v_rcp_f32_e32 v95, v95
	v_exp_f32_e32 v98, v98
	v_exp_f32_e32 v104, v104
	v_exp_f32_e32 v105, v105
	v_exp_f32_e32 v99, v99
	v_pk_mul_f32 v[92:93], v[92:93], v[94:95]
	v_pk_mul_f32 v[90:91], v[90:91], v[96:97]
	v_pk_fma_f32 v[94:95], v[102:103], v[104:105], v[102:103] op_sel_hi:[0,1,0]
	v_pk_fma_f32 v[96:97], v[102:103], v[98:99], v[102:103] op_sel_hi:[0,1,0]
	v_rcp_f32_e32 v96, v96
	v_rcp_f32_e32 v94, v94
	v_rcp_f32_e32 v95, v95
	v_rcp_f32_e32 v97, v97
	v_pk_mul_f32 v[66:67], v[70:71], v[66:67]
	v_pk_mul_f32 v[60:61], v[64:65], v[60:61]
	v_pk_mul_f32 v[86:87], v[84:85], v[94:95]
	v_pk_mul_f32 v[84:85], v[82:83], v[96:97]
	v_cvt_pk_bf16_f32 v82, v90, v91
	v_cvt_pk_bf16_f32 v83, v92, v93
	v_pk_mul_f32 v[58:59], v[62:63], v[58:59]
	v_cvt_pk_bf16_f32 v84, v84, v85
; __device__ __forceinline__ u32x4 pack8(const f32x4 a, const f32x4 b) { u32x4 w; w.x = cvt_pk_bf16(a[0], a[1]); w.y = cvt_pk_bf16(a[2], a[3]); w.z = cvt_pk_bf16(b[0], b[1]); w.w = cvt_pk_bf16(b[2], b[3]); return w; }
;     __device__ __forceinline__ void operator()(const f32x4 (&acc)[2][2][4][2], const Unit& u, int wr, int wc, int fr, int fq) const {
;     ...
; #pragma unroll
;         for (int ai = 0; ai < 2; ++ai)
; #pragma unroll
;             for (int m = 0; m < 4; ++m) { const int row = row0 + ai * HALF + m * 16; const float r = rs[ai][m]; f32x4 v[2];
;                 const float r2 = -LOG2E * r, ir2 = __builtin_amdgcn_rcpf(r * r);
; #pragma unroll
;                 for (int n = 0; n < 2; ++n) { const f32x4 gt = acc[ai][0][m][n], up = acc[ai][1][m][n];
;                     const f32x4 t = gt * r2, gu = gt * up; f32x4 ex = (f32x4){__builtin_amdgcn_exp2f(t[0]), __builtin_amdgcn_exp2f(t[1]), __builtin_amdgcn_exp2f(t[2]), __builtin_amdgcn_exp2f(t[3])};
;                     const f32x4 den = ex * ir2 + ir2; const f32x4 rc = (f32x4){__builtin_amdgcn_rcpf(den[0]), __builtin_amdgcn_rcpf(den[1]), __builtin_amdgcn_rcpf(den[2]), __builtin_amdgcn_rcpf(den[3])};
;                     v[n] = gu * rc; }
;                 *(u32x4*)(HM + (size_t)row * FF + col0) = pack8(v[0], v[1]); }
	v_cvt_pk_bf16_f32 v85, v86, v87
	v_lshl_add_u64 v[250:251], s[84:85], 0, v[250:251]
	global_store_dwordx4 v[250:251], v[82:85], off
	v_pk_mul_f32 v[52:53], v[56:57], v[52:53]
	v_pk_mul_f32 v[50:51], v[54:55], v[50:51]
	v_mul_f32_e32 v82, 0xbfb8aa3b, v171
	v_pk_mul_f32 v[86:87], v[80:81], v[82:83] op_sel_hi:[1,0]
	v_pk_mul_f32 v[88:89], v[78:79], v[82:83] op_sel_hi:[1,0]
	v_rcp_f32_e32 v84, v100
	v_exp_f32_e32 v88, v88
	v_exp_f32_e32 v86, v86
	v_exp_f32_e32 v87, v87
	v_exp_f32_e32 v89, v89
	v_pk_mul_f32 v[44:45], v[48:49], v[44:45]
	v_pk_mul_f32 v[42:43], v[46:47], v[42:43]
	v_pk_fma_f32 v[78:79], v[84:85], v[86:87], v[84:85] op_sel_hi:[0,1,0]
	v_pk_fma_f32 v[80:81], v[84:85], v[88:89], v[84:85] op_sel_hi:[0,1,0]
	v_pk_mul_f32 v[86:87], v[72:73], v[82:83] op_sel_hi:[1,0]
	v_pk_mul_f32 v[82:83], v[70:71], v[82:83] op_sel_hi:[1,0]
	v_rcp_f32_e32 v80, v80
	v_rcp_f32_e32 v81, v81
	v_rcp_f32_e32 v78, v78
	v_rcp_f32_e32 v79, v79
	v_exp_f32_e32 v82, v82
	v_exp_f32_e32 v86, v86
	v_exp_f32_e32 v87, v87
	v_exp_f32_e32 v83, v83
	v_pk_mul_f32 v[76:77], v[76:77], v[78:79]
	v_pk_mul_f32 v[74:75], v[74:75], v[80:81]
	v_pk_fma_f32 v[78:79], v[84:85], v[86:87], v[84:85] op_sel_hi:[0,1,0]
	v_pk_fma_f32 v[80:81], v[84:85], v[82:83], v[84:85] op_sel_hi:[0,1,0]
	v_rcp_f32_e32 v80, v80
	v_rcp_f32_e32 v78, v78
	v_rcp_f32_e32 v79, v79
	v_rcp_f32_e32 v81, v81
	v_pk_mul_f32 v[36:37], v[40:41], v[36:37]
	v_pk_mul_f32 v[34:35], v[38:39], v[34:35]
	v_pk_mul_f32 v[70:71], v[68:69], v[78:79]
	v_pk_mul_f32 v[68:69], v[66:67], v[80:81]
	v_cvt_pk_bf16_f32 v66, v74, v75
	v_cvt_pk_bf16_f32 v67, v76, v77
	v_pk_mul_f32 v[28:29], v[32:33], v[28:29]
	v_cvt_pk_bf16_f32 v68, v68, v69
	v_cvt_pk_bf16_f32 v69, v70, v71
	v_lshl_add_u64 v[250:251], s[84:85], 0, v[250:251]
	global_store_dwordx4 v[250:251], v[66:69], off
	v_pk_mul_f32 v[26:27], v[30:31], v[26:27]
	v_pk_mul_f32 v[20:21], v[24:25], v[20:21]
	v_mul_f32_e32 v66, 0xbfb8aa3b, v160
	v_pk_mul_f32 v[68:69], v[166:167], v[166:167]
	v_pk_mul_f32 v[72:73], v[64:65], v[66:67] op_sel_hi:[1,0]
	v_pk_mul_f32 v[74:75], v[62:63], v[66:67] op_sel_hi:[1,0]
	v_rcp_f32_e32 v70, v69
	v_exp_f32_e32 v74, v74
	v_exp_f32_e32 v72, v72
	v_exp_f32_e32 v73, v73
	v_exp_f32_e32 v75, v75
	v_pk_mul_f32 v[18:19], v[22:23], v[18:19]
	v_pk_mul_f32 v[12:13], v[16:17], v[12:13]
	v_pk_fma_f32 v[62:63], v[70:71], v[72:73], v[70:71] op_sel_hi:[0,1,0]
	v_pk_fma_f32 v[64:65], v[70:71], v[74:75], v[70:71] op_sel_hi:[0,1,0]
	v_pk_mul_f32 v[72:73], v[56:57], v[66:67] op_sel_hi:[1,0]
	v_pk_mul_f32 v[66:67], v[54:55], v[66:67] op_sel_hi:[1,0]
	v_rcp_f32_e32 v64, v64
	v_rcp_f32_e32 v65, v65
	v_rcp_f32_e32 v62, v62
	v_rcp_f32_e32 v63, v63
	v_exp_f32_e32 v66, v66
	v_exp_f32_e32 v72, v72
	v_exp_f32_e32 v73, v73
	v_exp_f32_e32 v67, v67
	v_pk_mul_f32 v[60:61], v[60:61], v[62:63]
	v_pk_mul_f32 v[58:59], v[58:59], v[64:65]
	v_pk_fma_f32 v[62:63], v[70:71], v[72:73], v[70:71] op_sel_hi:[0,1,0]
	v_pk_fma_f32 v[64:65], v[70:71], v[66:67], v[70:71] op_sel_hi:[0,1,0]
	v_rcp_f32_e32 v64, v64
	v_rcp_f32_e32 v62, v62
	v_rcp_f32_e32 v63, v63
	v_rcp_f32_e32 v65, v65
	v_pk_mul_f32 v[10:11], v[14:15], v[10:11]
	v_pk_mul_f32 v[4:5], v[8:9], v[4:5]
	v_pk_mul_f32 v[54:55], v[52:53], v[62:63]
	v_pk_mul_f32 v[52:53], v[50:51], v[64:65]
	v_cvt_pk_bf16_f32 v50, v58, v59
	v_cvt_pk_bf16_f32 v51, v60, v61
	v_pk_mul_f32 v[2:3], v[6:7], v[2:3]
	v_cvt_pk_bf16_f32 v52, v52, v53
	v_cvt_pk_bf16_f32 v53, v54, v55
	v_lshl_add_u64 v[250:251], s[86:87], 0, v[250:251]
	global_store_dwordx4 v[250:251], v[50:53], off
	s_andn2_b64 vcc, exec, s[2:3]
	s_nop 0
	v_mul_f32_e32 v50, 0xbfb8aa3b, v161
	v_pk_mul_f32 v[54:55], v[48:49], v[50:51] op_sel_hi:[1,0]
	v_pk_mul_f32 v[56:57], v[46:47], v[50:51] op_sel_hi:[1,0]
	v_rcp_f32_e32 v52, v68
	v_exp_f32_e32 v56, v56
	v_exp_f32_e32 v54, v54
	v_exp_f32_e32 v55, v55
	v_exp_f32_e32 v57, v57
	v_pk_fma_f32 v[46:47], v[52:53], v[54:55], v[52:53] op_sel_hi:[0,1,0]
	v_pk_fma_f32 v[48:49], v[52:53], v[56:57], v[52:53] op_sel_hi:[0,1,0]
; __device__ __forceinline__ u32x4 pack8(const f32x4 a, const f32x4 b) { u32x4 w; w.x = cvt_pk_bf16(a[0], a[1]); w.y = cvt_pk_bf16(a[2], a[3]); w.z = cvt_pk_bf16(b[0], b[1]); w.w = cvt_pk_bf16(b[2], b[3]); return w; }
;     __device__ __forceinline__ void operator()(const f32x4 (&acc)[2][2][4][2], const Unit& u, int wr, int wc, int fr, int fq) const {
;     ...
; #pragma unroll
;         for (int ai = 0; ai < 2; ++ai)
; #pragma unroll
;             for (int m = 0; m < 4; ++m) { const int row = row0 + ai * HALF + m * 16; const float r = rs[ai][m]; f32x4 v[2];
;                 const float r2 = -LOG2E * r, ir2 = __builtin_amdgcn_rcpf(r * r);
; #pragma unroll
;                 for (int n = 0; n < 2; ++n) { const f32x4 gt = acc[ai][0][m][n], up = acc[ai][1][m][n];
;                     const f32x4 t = gt * r2, gu = gt * up; f32x4 ex = (f32x4){__builtin_amdgcn_exp2f(t[0]), __builtin_amdgcn_exp2f(t[1]), __builtin_amdgcn_exp2f(t[2]), __builtin_amdgcn_exp2f(t[3])};
;                     const f32x4 den = ex * ir2 + ir2; const f32x4 rc = (f32x4){__builtin_amdgcn_rcpf(den[0]), __builtin_amdgcn_rcpf(den[1]), __builtin_amdgcn_rcpf(den[2]), __builtin_amdgcn_rcpf(den[3])};
;                     v[n] = gu * rc; }
;                 *(u32x4*)(HM + (size_t)row * FF + col0) = pack8(v[0], v[1]); }
	v_pk_mul_f32 v[54:55], v[40:41], v[50:51] op_sel_hi:[1,0]
	v_pk_mul_f32 v[50:51], v[38:39], v[50:51] op_sel_hi:[1,0]
	v_rcp_f32_e32 v48, v48
	v_rcp_f32_e32 v49, v49
	v_rcp_f32_e32 v46, v46
	v_rcp_f32_e32 v47, v47
	v_exp_f32_e32 v50, v50
	v_exp_f32_e32 v54, v54
	v_exp_f32_e32 v55, v55
	v_exp_f32_e32 v51, v51
	v_pk_mul_f32 v[44:45], v[44:45], v[46:47]
	v_pk_mul_f32 v[42:43], v[42:43], v[48:49]
	v_pk_fma_f32 v[46:47], v[52:53], v[54:55], v[52:53] op_sel_hi:[0,1,0]
	v_pk_fma_f32 v[48:49], v[52:53], v[50:51], v[52:53] op_sel_hi:[0,1,0]
	v_rcp_f32_e32 v48, v48
	v_rcp_f32_e32 v46, v46
	v_rcp_f32_e32 v47, v47
	v_rcp_f32_e32 v49, v49
	v_add_u32_e32 v40, 16, v148
	v_pk_mul_f32 v[38:39], v[36:37], v[46:47]
	v_pk_mul_f32 v[36:37], v[34:35], v[48:49]
	v_cvt_pk_bf16_f32 v34, v42, v43
	v_cvt_pk_bf16_f32 v35, v44, v45
	s_nop 0
	v_cvt_pk_bf16_f32 v36, v36, v37
	v_cvt_pk_bf16_f32 v37, v38, v39
	v_lshl_add_u64 v[250:251], s[84:85], 0, v[250:251]
	global_store_dwordx4 v[250:251], v[34:37], off
	s_nop 1
	v_mul_f32_e32 v34, 0xbfb8aa3b, v152
	v_pk_mul_f32 v[36:37], v[156:157], v[156:157]
	v_pk_mul_f32 v[40:41], v[32:33], v[34:35] op_sel_hi:[1,0]
	v_pk_mul_f32 v[42:43], v[30:31], v[34:35] op_sel_hi:[1,0]
	v_rcp_f32_e32 v38, v37
	v_exp_f32_e32 v42, v42
	v_exp_f32_e32 v40, v40
	v_exp_f32_e32 v41, v41
	v_exp_f32_e32 v43, v43
	v_pk_fma_f32 v[30:31], v[38:39], v[40:41], v[38:39] op_sel_hi:[0,1,0]
	v_pk_fma_f32 v[32:33], v[38:39], v[42:43], v[38:39] op_sel_hi:[0,1,0]
	v_pk_mul_f32 v[40:41], v[24:25], v[34:35] op_sel_hi:[1,0]
	v_pk_mul_f32 v[34:35], v[22:23], v[34:35] op_sel_hi:[1,0]
	v_rcp_f32_e32 v32, v32
	v_rcp_f32_e32 v33, v33
	v_rcp_f32_e32 v30, v30
	v_rcp_f32_e32 v31, v31
	v_exp_f32_e32 v34, v34
	v_exp_f32_e32 v40, v40
	v_exp_f32_e32 v41, v41
	v_exp_f32_e32 v35, v35
	v_pk_mul_f32 v[28:29], v[28:29], v[30:31]
	v_pk_mul_f32 v[26:27], v[26:27], v[32:33]
	v_pk_fma_f32 v[30:31], v[38:39], v[40:41], v[38:39] op_sel_hi:[0,1,0]
	v_pk_fma_f32 v[32:33], v[38:39], v[34:35], v[38:39] op_sel_hi:[0,1,0]
	v_rcp_f32_e32 v32, v32
	v_rcp_f32_e32 v30, v30
	v_rcp_f32_e32 v31, v31
	v_rcp_f32_e32 v33, v33
	v_add_u32_e32 v24, 32, v148
	v_pk_mul_f32 v[22:23], v[20:21], v[30:31]
	v_pk_mul_f32 v[20:21], v[18:19], v[32:33]
	v_cvt_pk_bf16_f32 v18, v26, v27
	v_cvt_pk_bf16_f32 v19, v28, v29
	s_nop 0
	v_cvt_pk_bf16_f32 v20, v20, v21
	v_cvt_pk_bf16_f32 v21, v22, v23
	v_lshl_add_u64 v[250:251], s[84:85], 0, v[250:251]
	global_store_dwordx4 v[250:251], v[18:21], off
	s_nop 1
	v_mul_f32_e32 v18, 0xbfb8aa3b, v153
	v_pk_mul_f32 v[22:23], v[16:17], v[18:19] op_sel_hi:[1,0]
	v_pk_mul_f32 v[24:25], v[14:15], v[18:19] op_sel_hi:[1,0]
	v_rcp_f32_e32 v20, v36
	v_exp_f32_e32 v24, v24
	v_exp_f32_e32 v22, v22
	v_exp_f32_e32 v23, v23
	v_exp_f32_e32 v25, v25
	v_pk_fma_f32 v[14:15], v[20:21], v[22:23], v[20:21] op_sel_hi:[0,1,0]
	v_pk_fma_f32 v[16:17], v[20:21], v[24:25], v[20:21] op_sel_hi:[0,1,0]
	v_pk_mul_f32 v[22:23], v[8:9], v[18:19] op_sel_hi:[1,0]
	v_pk_mul_f32 v[18:19], v[6:7], v[18:19] op_sel_hi:[1,0]
	v_rcp_f32_e32 v16, v16
	v_rcp_f32_e32 v17, v17
	v_rcp_f32_e32 v14, v14
	v_rcp_f32_e32 v15, v15
	v_exp_f32_e32 v18, v18
	v_exp_f32_e32 v22, v22
	v_exp_f32_e32 v23, v23
	v_exp_f32_e32 v19, v19
	v_pk_mul_f32 v[12:13], v[12:13], v[14:15]
	v_pk_mul_f32 v[10:11], v[10:11], v[16:17]
	v_pk_fma_f32 v[14:15], v[20:21], v[22:23], v[20:21] op_sel_hi:[0,1,0]
	v_pk_fma_f32 v[16:17], v[20:21], v[18:19], v[20:21] op_sel_hi:[0,1,0]
	v_rcp_f32_e32 v16, v16
	v_rcp_f32_e32 v14, v14
	v_rcp_f32_e32 v15, v15
	v_rcp_f32_e32 v17, v17
	v_add_u32_e32 v8, 48, v148
	v_pk_mul_f32 v[6:7], v[4:5], v[14:15]
	v_pk_mul_f32 v[4:5], v[2:3], v[16:17]
	v_cvt_pk_bf16_f32 v2, v10, v11
	v_cvt_pk_bf16_f32 v3, v12, v13
	s_nop 0
	v_cvt_pk_bf16_f32 v4, v4, v5
	v_cvt_pk_bf16_f32 v5, v6, v7
	s_mov_b64 s[0:1], -1
	v_lshl_add_u64 v[250:251], s[84:85], 0, v[250:251]
	global_store_dwordx4 v[250:251], v[2:5], off
	s_cbranch_vccnz .LBB0_734
	s_andn2_b64 vcc, exec, s[12:13]
	s_cbranch_vccnz .LBB0_733
	s_barrier
	s_branch .LBB0_733
